# v61 + s_setprio 1 for waves 4-7 scoped to the staggered GEMM K-loops
# baseline (speedup 1.0000x reference)
; template <int MODE, bool SWAP, int MT>
; DI void gemm_tile(const int wv_, const Params& p, const u16* __restrict__ A, const u16* __restrict__ Bt, int brow, int bcol, char* smem, const float* gnext) {
;     ...
;   for (int t = 0; t < 32; ++t) {
;     asm volatile("s_waitcnt vmcnt(0)" ::: "memory");
;     __syncthreads();
;     if (t + 1 < 32) stage(t + 1, (t + 1) & 1);
.Lpp_Bent_1:
	s_setprio 1

; template <int MODE, bool SWAP, int MT>
; DI void gemm_tile(const int wv_, const Params& p, const u16* __restrict__ A, const u16* __restrict__ Bt, int brow, int bcol, char* smem, const float* gnext) {
;     ...
;     for (int m = MH; m < MT; ++m)
; #pragma unroll
;       for (int n = 0; n < 4; ++n)
;         acc[m][n] = SWAP ? __builtin_amdgcn_mfma_f32_16x16x32_bf16(Bf[n], Af[m], acc[m][n], 0, 0, 0)
;                          : __builtin_amdgcn_mfma_f32_16x16x32_bf16(Af[m], Bf[n], acc[m][n], 0, 0, 0);
.Lpp_lastB_1:
	v_mfma_f32_16x16x32_bf16 v[64:67], v[80:83], v[96:99], v[64:67]
	v_mfma_f32_16x16x32_bf16 v[60:63], v[84:87], v[96:99], v[60:63]
	v_mfma_f32_16x16x32_bf16 v[56:59], v[88:91], v[96:99], v[56:59]
	v_mfma_f32_16x16x32_bf16 v[52:55], v[92:95], v[96:99], v[52:55]
	v_mfma_f32_16x16x32_bf16 v[48:51], v[80:83], v[100:103], v[48:51]
	v_mfma_f32_16x16x32_bf16 v[40:43], v[84:87], v[100:103], v[40:43]
	v_mfma_f32_16x16x32_bf16 v[36:39], v[88:91], v[100:103], v[36:39]
	v_mfma_f32_16x16x32_bf16 v[44:47], v[92:95], v[100:103], v[44:47]
	v_mfma_f32_16x16x32_bf16 v[32:35], v[80:83], v[104:107], v[32:35]
	v_mfma_f32_16x16x32_bf16 v[28:31], v[84:87], v[104:107], v[28:31]
	v_mfma_f32_16x16x32_bf16 v[24:27], v[88:91], v[104:107], v[24:27]
	v_mfma_f32_16x16x32_bf16 v[20:23], v[92:95], v[104:107], v[20:23]
	v_mfma_f32_16x16x32_bf16 v[16:19], v[80:83], v[108:111], v[16:19]
	v_mfma_f32_16x16x32_bf16 v[12:15], v[84:87], v[108:111], v[12:15]
	v_mfma_f32_16x16x32_bf16 v[8:11], v[88:91], v[108:111], v[8:11]
	v_mfma_f32_16x16x32_bf16 v[4:7], v[92:95], v[108:111], v[4:7]
	s_mov_b32 s0, s1
	s_setprio 0

; template <int MODE, bool SWAP, int MT>
; DI void gemm_tile(const int wv_, const Params& p, const u16* __restrict__ A, const u16* __restrict__ Bt, int brow, int bcol, char* smem, const float* gnext) {
;     ...
;     for (int m = MH; m < MT; ++m)
; #pragma unroll
;       for (int n = 0; n < 4; ++n)
;         acc[m][n] = SWAP ? __builtin_amdgcn_mfma_f32_16x16x32_bf16(Bf[n], Af[m], acc[m][n], 0, 0, 0)
;                          : __builtin_amdgcn_mfma_f32_16x16x32_bf16(Af[m], Bf[n], acc[m][n], 0, 0, 0);
.Lpp_lastB_2:
	v_mfma_f32_16x16x32_bf16 v[64:67], v[96:99], v[80:83], v[64:67]
	v_mfma_f32_16x16x32_bf16 v[60:63], v[96:99], v[84:87], v[60:63]
	v_mfma_f32_16x16x32_bf16 v[56:59], v[96:99], v[88:91], v[56:59]
	v_mfma_f32_16x16x32_bf16 v[52:55], v[96:99], v[92:95], v[52:55]
	v_mfma_f32_16x16x32_bf16 v[48:51], v[100:103], v[80:83], v[48:51]
	v_mfma_f32_16x16x32_bf16 v[44:47], v[100:103], v[84:87], v[44:47]
	v_mfma_f32_16x16x32_bf16 v[40:43], v[100:103], v[88:91], v[40:43]
	v_mfma_f32_16x16x32_bf16 v[36:39], v[100:103], v[92:95], v[36:39]
	v_mfma_f32_16x16x32_bf16 v[32:35], v[104:107], v[80:83], v[32:35]
	v_mfma_f32_16x16x32_bf16 v[28:31], v[104:107], v[84:87], v[28:31]
	v_mfma_f32_16x16x32_bf16 v[24:27], v[104:107], v[88:91], v[24:27]
	v_mfma_f32_16x16x32_bf16 v[20:23], v[104:107], v[92:95], v[20:23]
	v_mfma_f32_16x16x32_bf16 v[16:19], v[108:111], v[80:83], v[16:19]
	v_mfma_f32_16x16x32_bf16 v[12:15], v[108:111], v[84:87], v[12:15]
	v_mfma_f32_16x16x32_bf16 v[8:11], v[108:111], v[88:91], v[8:11]
	v_mfma_f32_16x16x32_bf16 v[4:7], v[108:111], v[92:95], v[4:7]
	s_mov_b32 s0, s1
	s_setprio 0

; template <int MODE, bool SWAP, int MT>
; DI void gemm_tile(const int wv_, const Params& p, const u16* __restrict__ A, const u16* __restrict__ Bt, int brow, int bcol, char* smem, const float* gnext) {
;     ...
; #pragma unroll
;     for (int m = 0; m < MH; ++m)
; #pragma unroll
;       for (int n = 0; n < 4; ++n)
;         acc[m][n] = SWAP ? __builtin_amdgcn_mfma_f32_16x16x32_bf16(Bf[n], Af[m], acc[m][n], 0, 0, 0)
;                          : __builtin_amdgcn_mfma_f32_16x16x32_bf16(Af[m], Bf[n], acc[m][n], 0, 0, 0);
;     __builtin_amdgcn_sched_barrier(0);
; #pragma unroll
;     for (int m = MH; m < MT; ++m)
; #pragma unroll
;       for (int n = 0; n < 4; ++n)
;         acc[m][n] = SWAP ? __builtin_amdgcn_mfma_f32_16x16x32_bf16(Bf[n], Af[m], acc[m][n], 0, 0, 0)
;                          : __builtin_amdgcn_mfma_f32_16x16x32_bf16(Af[m], Bf[n], acc[m][n], 0, 0, 0);
.Lpp_lastB_3:
	v_mfma_f32_16x16x32_bf16 v[64:67], v[80:83], v[96:99], v[64:67]
	v_mfma_f32_16x16x32_bf16 v[60:63], v[84:87], v[96:99], v[60:63]
	v_mfma_f32_16x16x32_bf16 v[56:59], v[88:91], v[96:99], v[56:59]
	v_mfma_f32_16x16x32_bf16 v[52:55], v[92:95], v[96:99], v[52:55]
	v_mfma_f32_16x16x32_bf16 v[48:51], v[80:83], v[100:103], v[48:51]
	v_mfma_f32_16x16x32_bf16 v[40:43], v[84:87], v[100:103], v[40:43]
	v_mfma_f32_16x16x32_bf16 v[36:39], v[88:91], v[100:103], v[36:39]
	v_mfma_f32_16x16x32_bf16 v[44:47], v[92:95], v[100:103], v[44:47]
	v_mfma_f32_16x16x32_bf16 v[32:35], v[80:83], v[104:107], v[32:35]
	v_mfma_f32_16x16x32_bf16 v[28:31], v[84:87], v[104:107], v[28:31]
	v_mfma_f32_16x16x32_bf16 v[24:27], v[88:91], v[104:107], v[24:27]
	v_mfma_f32_16x16x32_bf16 v[20:23], v[92:95], v[104:107], v[20:23]
	v_mfma_f32_16x16x32_bf16 v[16:19], v[80:83], v[108:111], v[16:19]
	v_mfma_f32_16x16x32_bf16 v[12:15], v[84:87], v[108:111], v[12:15]
	v_mfma_f32_16x16x32_bf16 v[8:11], v[88:91], v[108:111], v[8:11]
	v_mfma_f32_16x16x32_bf16 v[4:7], v[92:95], v[108:111], v[4:7]
	s_mov_b32 s1, s6
	s_setprio 0

; template <int MODE, bool SWAP, int MT>
; DI void gemm_tile(const int wv_, const Params& p, const u16* __restrict__ A, const u16* __restrict__ Bt, int brow, int bcol, char* smem, const float* gnext) {
;     ...
; #pragma unroll
;     for (int m = 0; m < MH; ++m)
; #pragma unroll
;       for (int n = 0; n < 4; ++n)
;         acc[m][n] = SWAP ? __builtin_amdgcn_mfma_f32_16x16x32_bf16(Bf[n], Af[m], acc[m][n], 0, 0, 0)
;                          : __builtin_amdgcn_mfma_f32_16x16x32_bf16(Af[m], Bf[n], acc[m][n], 0, 0, 0);
;     __builtin_amdgcn_sched_barrier(0);
; #pragma unroll
;     for (int m = MH; m < MT; ++m)
; #pragma unroll
;       for (int n = 0; n < 4; ++n)
;         acc[m][n] = SWAP ? __builtin_amdgcn_mfma_f32_16x16x32_bf16(Bf[n], Af[m], acc[m][n], 0, 0, 0)
;                          : __builtin_amdgcn_mfma_f32_16x16x32_bf16(Af[m], Bf[n], acc[m][n], 0, 0, 0);
.Lpp_lastB_4:
	v_mfma_f32_16x16x32_bf16 v[64:67], v[80:83], v[96:99], v[64:67]
	v_mfma_f32_16x16x32_bf16 v[60:63], v[84:87], v[96:99], v[60:63]
	v_mfma_f32_16x16x32_bf16 v[56:59], v[88:91], v[96:99], v[56:59]
	v_mfma_f32_16x16x32_bf16 v[52:55], v[92:95], v[96:99], v[52:55]
	v_mfma_f32_16x16x32_bf16 v[48:51], v[80:83], v[100:103], v[48:51]
	v_mfma_f32_16x16x32_bf16 v[44:47], v[84:87], v[100:103], v[44:47]
	v_mfma_f32_16x16x32_bf16 v[40:43], v[88:91], v[100:103], v[40:43]
	v_mfma_f32_16x16x32_bf16 v[36:39], v[92:95], v[100:103], v[36:39]
	v_mfma_f32_16x16x32_bf16 v[32:35], v[80:83], v[104:107], v[32:35]
	v_mfma_f32_16x16x32_bf16 v[28:31], v[84:87], v[104:107], v[28:31]
	v_mfma_f32_16x16x32_bf16 v[24:27], v[88:91], v[104:107], v[24:27]
	v_mfma_f32_16x16x32_bf16 v[20:23], v[92:95], v[104:107], v[20:23]
	v_mfma_f32_16x16x32_bf16 v[16:19], v[80:83], v[108:111], v[16:19]
	v_mfma_f32_16x16x32_bf16 v[12:15], v[84:87], v[108:111], v[12:15]
	v_mfma_f32_16x16x32_bf16 v[8:11], v[88:91], v[108:111], v[8:11]
	v_mfma_f32_16x16x32_bf16 v[4:7], v[92:95], v[108:111], v[4:7]
	s_mov_b32 s1, s2
	s_setprio 0
